# MLA stagger + no static priority for waves 0-3
# speedup vs baseline: 1.0060x; 1.0060x over previous
.LBB0_518:
	s_nop 0
	v_mov_b32_e32 v4, v193
	s_nop 0
	v_readfirstlane_b32 s0, v4
	s_ashr_i32 s16, s0, 6
	s_cmp_gt_i32 s16, 3
	s_cbranch_scc1 .LBB0_520
	s_setprio 0
